# L2 warm-up loads of the first two K-tiles (and RS table) issued before the P1/P7 table fills
# baseline (speedup 1.0000x reference)
.LBB0_303:
	s_waitcnt lgkmcnt(0)
	s_add_u32 s18, s26, 0x6400000
	s_addc_u32 s19, s27, 0
	s_add_u32 s10, s26, 0x8400000
	s_addc_u32 s11, s27, 0
	s_add_u32 s38, s26, 0xc400000
	s_addc_u32 s39, s27, 0
	s_cmp_lt_i32 s28, 2
	s_cselect_b64 s[14:15], -1, 0
	s_and_b64 s[20:21], s[14:15], s[0:1]
	s_mov_b64 s[4:5], -1
	s_mov_b64 s[16:17], 0
	s_andn2_b64 vcc, exec, s[20:21]
	s_mov_b64 s[14:15], 0
	s_cbranch_vccnz .LBB0_339
	s_and_b32 s98, s2, 7
	s_mul_i32 s98, s98, 0x60
	s_lshr_b32 s99, s2, 3
	s_add_i32 s98, s98, s99
	s_mul_hi_u32 s99, s98, 0x1555556
	s_mul_i32 s100, s99, 0xc0
	s_sub_i32 s98, s98, s100
	s_lshl_b32 s99, s99, 3
	s_and_b32 s100, s98, 7
	s_add_i32 s99, s99, s100
	s_lshr_b32 s98, s98, 3
	v_readfirstlane_b32 s101, v208
	v_and_b32_e32 v238, 0xff, v208
	v_lshlrev_b32_e32 v238, 12, v238
	s_cmpk_lt_u32 s101, 0x100
	s_cselect_b32 s100, s98, s99
	s_cselect_b32 s98, s56, s18
	s_cselect_b32 s99, s57, s19
	s_lshl_b32 s100, s100, 20
	s_add_u32 s98, s98, s100
	s_addc_u32 s99, s99, 0
	global_load_dword v239, v238, s[98:99]
	global_load_dword v239, v238, s[98:99] offset:128
	s_add_u32 s98, s26, 0xfc04000
	s_addc_u32 s99, s27, 0
	v_lshlrev_b32_e32 v238, 7, v208
	global_load_dword v239, v238, s[98:99]
	v_and_b32_e32 v2, 0xff, v208
	v_lshrrev_b32_e32 v5, 8, v208
	v_lshlrev_b32_e32 v0, 2, v2
	s_add_u32 s4, s26, 0xfc04000
	v_lshl_or_b32 v0, v5, 10, v0
	s_addc_u32 s5, s27, 0
	s_ashr_i32 s3, s2, 31
	v_add_u32_e32 v0, 0, v0
	s_ashr_i32 s15, s30, 31
	s_mov_b32 s14, s30
	v_add_u32_e32 v4, 0x20000, v0
	v_mov_b64_e32 v[0:1], s[2:3]
	v_add_u32_e32 v3, -2, v5
	v_mad_i64_i32 v[0:1], s[0:1], v5, s30, v[0:1]
	s_lshl_b64 s[40:41], s[14:15], 1
	s_mov_b64 s[36:37], 0
	s_mov_b64 s[60:61], 0x300
	s_mov_b32 s64, 0x2aaaaaab
	s_movk_i32 s65, 0xc0
	v_mov_b32_e32 v5, 0x60
	v_mov_b32_e32 v6, 0x61
	s_branch .LBB0_306

.LBB0_618:
	s_add_u32 s8, s26, 0x4e00000
	s_addc_u32 s9, s27, 0
	s_cmp_lt_i32 s28, 8
	s_cselect_b64 s[0:1], -1, 0
	s_cmp_gt_i32 s29, 7
	s_cselect_b64 s[4:5], -1, 0
	s_and_b64 s[12:13], s[0:1], s[4:5]
	s_andn2_b64 vcc, exec, s[12:13]
	s_cbranch_vccnz .LBB0_653
	s_and_b32 s98, s2, 7
	s_mul_i32 s98, s98, 0xb0
	s_lshr_b32 s99, s2, 3
	s_add_i32 s98, s98, s99
	s_mul_hi_u32 s99, s98, 0xba2e8c
	s_mul_i32 s100, s99, 0x160
	s_sub_i32 s98, s98, s100
	s_lshl_b32 s99, s99, 3
	s_and_b32 s100, s98, 7
	s_add_i32 s99, s99, s100
	s_lshr_b32 s98, s98, 3
	v_readfirstlane_b32 s101, v208
	v_and_b32_e32 v238, 0xff, v208
	v_lshlrev_b32_e32 v238, 12, v238
	s_cmpk_lt_u32 s101, 0x100
	s_cselect_b32 s100, s98, s99
	s_cselect_b32 s98, s52, s10
	s_cselect_b32 s99, s53, s11
	s_lshl_b32 s100, s100, 20
	s_add_u32 s98, s98, s100
	s_addc_u32 s99, s99, 0
	global_load_dword v239, v238, s[98:99]
	global_load_dword v239, v238, s[98:99] offset:128
	s_ashr_i32 s3, s2, 31
	v_lshrrev_b32_e32 v64, 8, v208
	s_waitcnt lgkmcnt(0)
	v_mov_b64_e32 v[0:1], s[2:3]
	v_mad_i64_i32 v[2:3], s[0:1], v64, s30, v[0:1]
	s_mov_b64 s[4:5], 0x580
	s_ashr_i32 s50, s30, 31
	v_and_b32_e32 v96, 0xff, v208
	v_cmp_gt_i64_e32 vcc, s[4:5], v[2:3]
	s_and_saveexec_b64 s[6:7], vcc
	s_cbranch_execz .LBB0_621
	v_ashrrev_i32_e32 v0, 31, v2
	v_lshrrev_b32_e32 v0, 29, v0
	v_add_u32_e32 v0, v2, v0
	v_ashrrev_i32_e32 v1, 3, v0
	v_and_b32_e32 v0, -8, v0
	v_sub_u32_e32 v0, v2, v0
	v_mov_b32_e32 v2, 0xb0
	v_mov_b32_e32 v3, 0xb1
	v_cmp_gt_i32_e64 s[0:1], 0, v0
	s_nop 1
	v_cndmask_b32_e64 v2, v2, v3, s[0:1]
	v_mul_lo_u32 v0, v0, v2
	v_add_u32_e32 v0, v0, v1
	s_mov_b32 s0, 0x2e8ba2e9
	v_mul_hi_i32 v1, v0, s0
	v_lshrrev_b32_e32 v2, 31, v1
	v_ashrrev_i32_e32 v1, 6, v1
	v_add_u32_e32 v1, v1, v2
	v_lshlrev_b32_e32 v2, 3, v1
	v_sub_u32_e32 v3, 32, v2
	v_min_i32_e32 v3, 8, v3
	v_sub_u32_e32 v4, 0, v3
	v_max_i32_e32 v3, v3, v4
	v_cvt_f32_u32_e32 v4, v3
	v_mul_i32_i24_e32 v1, 0x160, v1
	v_sub_u32_e32 v0, v0, v1
	v_sub_u32_e32 v5, 0, v0
	v_rcp_iflag_f32_e32 v4, v4
	v_ashrrev_i32_e32 v1, 31, v0
	v_max_i32_e32 v0, v0, v5
	v_sub_u32_e32 v5, 0, v3
	v_mul_f32_e32 v4, 0x4f7ffffe, v4
	v_cvt_u32_f32_e32 v4, v4
	v_mul_lo_u32 v5, v5, v4
	v_mul_hi_u32 v5, v4, v5
	v_add_u32_e32 v4, v4, v5
	v_mul_hi_u32 v4, v0, v4
	v_mul_lo_u32 v4, v4, v3
	v_sub_u32_e32 v0, v0, v4
	v_sub_u32_e32 v4, v0, v3
	v_cmp_ge_u32_e64 s[0:1], v0, v3
	s_nop 1
	v_cndmask_b32_e64 v0, v0, v4, s[0:1]
	v_sub_u32_e32 v4, v0, v3
	v_cmp_ge_u32_e64 s[0:1], v0, v3
	s_nop 1
	v_cndmask_b32_e64 v0, v0, v4, s[0:1]
	v_xor_b32_e32 v0, v0, v1
	v_sub_u32_e32 v0, v0, v1
	v_add_u32_e32 v0, v2, v0
	v_lshl_or_b32 v0, v0, 8, v96
	v_ashrrev_i32_e32 v1, 31, v0
	v_lshlrev_b64 v[0:1], 7, v[0:1]
	v_lshl_add_u64 v[32:33], s[26:27], 0, v[0:1]
	global_load_dwordx4 v[8:11], v[32:33], off offset:48
	global_load_dwordx4 v[16:19], v[32:33], off offset:32
	global_load_dwordx4 v[24:27], v[32:33], off offset:16
	global_load_dwordx4 v[28:31], v[32:33], off
	global_load_dwordx4 v[0:3], v[32:33], off offset:112
	global_load_dwordx4 v[4:7], v[32:33], off offset:96
	global_load_dwordx4 v[12:15], v[32:33], off offset:80
	global_load_dwordx4 v[20:23], v[32:33], off offset:64
